# G1 K-loop: LDS-DMA pieces use saddr form (SGPR base + 32-bit VGPR offset), 16 per-piece 64-bit VALU address adds removed
# baseline (speedup 1.0000x reference)
.LBB0_120:
	s_add_u32 s8, s50, 0xfffc0080
	s_addc_u32 s9, s51, -1
	s_add_i32 s10, 0, 0x10000
	s_cmp_eq_u32 s72, 12
	s_cselect_b32 s57, s43, s9
	s_cselect_b32 s56, s66, s8
	v_add_u32_e32 v140, s10, v143
	s_cselect_b32 s55, s41, s69
	s_cselect_b32 s54, s67, s68
	s_add_i32 s11, 0, 0x14000
	ds_read_b128 v[146:149], v140
	ds_read_b128 v[150:153], v140 offset:1024
	ds_read_b128 v[154:157], v140 offset:2048
	ds_read_b128 v[158:161], v140 offset:3072
	v_add_u32_e32 v140, s11, v143
	ds_read_b128 v[162:165], v140
	ds_read_b128 v[166:169], v140 offset:1024
	ds_read_b128 v[170:173], v140 offset:2048
	ds_read_b128 v[174:177], v140 offset:3072
	s_add_i32 m0, s52, 0x1c000
	s_nop 0
	global_load_lds_dwordx4 v0, s[100:101]
	s_add_i32 m0, s52, 0x1e000
	s_nop 0
	global_load_lds_dwordx4 v130, s[100:101]
	s_add_i32 m0, s53, 0xc000
	ds_read_b128 v[178:181], v145
	ds_read_b128 v[182:185], v145 offset:1024
	ds_read_b128 v[224:227], v145 offset:2048
	ds_read_b128 v[228:231], v145 offset:3072
	ds_read_b128 v[232:235], v145 offset:4096
	ds_read_b128 v[236:239], v145 offset:5120
	ds_read_b128 v[240:243], v145 offset:6144
	ds_read_b128 v[244:247], v145 offset:7168
	global_load_lds_dwordx4 v136, s[50:51]
	s_add_i32 m0, s53, 0xe000
	s_nop 0
	global_load_lds_dwordx4 v138, s[50:51]
	s_waitcnt vmcnt(8)
	s_waitcnt lgkmcnt(0)
	s_barrier
	s_setprio 1
	s_waitcnt lgkmcnt(0)
	v_mfma_f32_16x16x32_bf16 v[126:129], v[146:149], v[178:181], v[126:129]
	v_mfma_f32_16x16x32_bf16 v[118:121], v[154:157], v[178:181], v[118:121]
	v_mfma_f32_16x16x32_bf16 v[110:113], v[146:149], v[224:227], v[110:113]
	v_mfma_f32_16x16x32_bf16 v[102:105], v[154:157], v[224:227], v[102:105]
	v_mfma_f32_16x16x32_bf16 v[94:97], v[146:149], v[232:235], v[94:97]
	v_mfma_f32_16x16x32_bf16 v[86:89], v[154:157], v[232:235], v[86:89]
	v_mfma_f32_16x16x32_bf16 v[78:81], v[146:149], v[240:243], v[78:81]
	v_mfma_f32_16x16x32_bf16 v[70:73], v[154:157], v[240:243], v[70:73]
	v_mfma_f32_16x16x32_bf16 v[126:129], v[150:153], v[182:185], v[126:129]
	v_mfma_f32_16x16x32_bf16 v[118:121], v[158:161], v[182:185], v[118:121]
	v_mfma_f32_16x16x32_bf16 v[110:113], v[150:153], v[228:231], v[110:113]
	v_mfma_f32_16x16x32_bf16 v[102:105], v[158:161], v[228:231], v[102:105]
	v_mfma_f32_16x16x32_bf16 v[94:97], v[150:153], v[236:239], v[94:97]
	v_mfma_f32_16x16x32_bf16 v[86:89], v[158:161], v[236:239], v[86:89]
	v_mfma_f32_16x16x32_bf16 v[78:81], v[150:153], v[244:247], v[78:81]
	v_mfma_f32_16x16x32_bf16 v[70:73], v[158:161], v[244:247], v[70:73]
	s_setprio 0
	s_setprio 1
	v_mfma_f32_16x16x32_bf16 v[122:125], v[162:165], v[178:181], v[122:125]
	v_mfma_f32_16x16x32_bf16 v[114:117], v[170:173], v[178:181], v[114:117]
	v_mfma_f32_16x16x32_bf16 v[106:109], v[162:165], v[224:227], v[106:109]
	v_mfma_f32_16x16x32_bf16 v[98:101], v[170:173], v[224:227], v[98:101]
	v_mfma_f32_16x16x32_bf16 v[90:93], v[162:165], v[232:235], v[90:93]
	v_mfma_f32_16x16x32_bf16 v[82:85], v[170:173], v[232:235], v[82:85]
	v_mfma_f32_16x16x32_bf16 v[74:77], v[162:165], v[240:243], v[74:77]
	v_mfma_f32_16x16x32_bf16 v[66:69], v[170:173], v[240:243], v[66:69]
	v_mfma_f32_16x16x32_bf16 v[122:125], v[166:169], v[182:185], v[122:125]
	v_mfma_f32_16x16x32_bf16 v[114:117], v[174:177], v[182:185], v[114:117]
	v_mfma_f32_16x16x32_bf16 v[106:109], v[166:169], v[228:231], v[106:109]
	v_mfma_f32_16x16x32_bf16 v[98:101], v[174:177], v[228:231], v[98:101]
	v_mfma_f32_16x16x32_bf16 v[90:93], v[166:169], v[236:239], v[90:93]
	v_mfma_f32_16x16x32_bf16 v[82:85], v[174:177], v[236:239], v[82:85]
	v_mfma_f32_16x16x32_bf16 v[74:77], v[166:169], v[244:247], v[74:77]
	v_mfma_f32_16x16x32_bf16 v[66:69], v[174:177], v[244:247], v[66:69]
	s_setprio 0
	s_barrier
	s_add_i32 s8, s10, s52
	s_mov_b32 m0, s8
	ds_read_b128 v[178:181], v145 offset:16384
	ds_read_b128 v[182:185], v145 offset:17408
	ds_read_b128 v[224:227], v145 offset:18432
	ds_read_b128 v[228:231], v145 offset:19456
	ds_read_b128 v[232:235], v145 offset:20480
	ds_read_b128 v[236:239], v145 offset:21504
	ds_read_b128 v[240:243], v145 offset:22528
	ds_read_b128 v[244:247], v145 offset:23552
	global_load_lds_dwordx4 v0, s[54:55]
	s_add_i32 m0, s8, 0x2000
	s_nop 0
	global_load_lds_dwordx4 v130, s[54:55]
	s_mov_b32 m0, s53
	s_nop 0
	global_load_lds_dwordx4 v134, s[56:57]
	s_mov_b32 m0, s58
	s_nop 0
	global_load_lds_dwordx4 v132, s[56:57]
	s_waitcnt vmcnt(6)
	s_waitcnt lgkmcnt(0)
	s_barrier
	s_setprio 1
	s_waitcnt lgkmcnt(0)
	v_mfma_f32_16x16x32_bf16 v[62:65], v[146:149], v[178:181], v[62:65]
	v_mfma_f32_16x16x32_bf16 v[54:57], v[154:157], v[178:181], v[54:57]
	v_mfma_f32_16x16x32_bf16 v[46:49], v[146:149], v[224:227], v[46:49]
	v_mfma_f32_16x16x32_bf16 v[38:41], v[154:157], v[224:227], v[38:41]
	v_mfma_f32_16x16x32_bf16 v[30:33], v[146:149], v[232:235], v[30:33]
	v_mfma_f32_16x16x32_bf16 v[22:25], v[154:157], v[232:235], v[22:25]
	v_mfma_f32_16x16x32_bf16 v[14:17], v[146:149], v[240:243], v[14:17]
	v_mfma_f32_16x16x32_bf16 v[6:9], v[154:157], v[240:243], v[6:9]
	v_mfma_f32_16x16x32_bf16 v[62:65], v[150:153], v[182:185], v[62:65]
	v_mfma_f32_16x16x32_bf16 v[54:57], v[158:161], v[182:185], v[54:57]
	v_mfma_f32_16x16x32_bf16 v[46:49], v[150:153], v[228:231], v[46:49]
	v_mfma_f32_16x16x32_bf16 v[38:41], v[158:161], v[228:231], v[38:41]
	v_mfma_f32_16x16x32_bf16 v[30:33], v[150:153], v[236:239], v[30:33]
	v_mfma_f32_16x16x32_bf16 v[22:25], v[158:161], v[236:239], v[22:25]
	v_mfma_f32_16x16x32_bf16 v[14:17], v[150:153], v[244:247], v[14:17]
	v_mfma_f32_16x16x32_bf16 v[6:9], v[158:161], v[244:247], v[6:9]
	s_setprio 0
	s_setprio 1
	v_mfma_f32_16x16x32_bf16 v[58:61], v[162:165], v[178:181], v[58:61]
	v_mfma_f32_16x16x32_bf16 v[50:53], v[170:173], v[178:181], v[50:53]
	v_mfma_f32_16x16x32_bf16 v[42:45], v[162:165], v[224:227], v[42:45]
	v_mfma_f32_16x16x32_bf16 v[34:37], v[170:173], v[224:227], v[34:37]
	v_mfma_f32_16x16x32_bf16 v[26:29], v[162:165], v[232:235], v[26:29]
	v_mfma_f32_16x16x32_bf16 v[18:21], v[170:173], v[232:235], v[18:21]
	v_mfma_f32_16x16x32_bf16 v[10:13], v[162:165], v[240:243], v[10:13]
	v_mfma_f32_16x16x32_bf16 v[2:5], v[170:173], v[240:243], v[2:5]
	v_mfma_f32_16x16x32_bf16 v[58:61], v[166:169], v[182:185], v[58:61]
	v_mfma_f32_16x16x32_bf16 v[50:53], v[174:177], v[182:185], v[50:53]
	v_mfma_f32_16x16x32_bf16 v[42:45], v[166:169], v[228:231], v[42:45]
	v_mfma_f32_16x16x32_bf16 v[34:37], v[174:177], v[228:231], v[34:37]
	v_mfma_f32_16x16x32_bf16 v[26:29], v[166:169], v[236:239], v[26:29]
	v_mfma_f32_16x16x32_bf16 v[18:21], v[174:177], v[236:239], v[18:21]
	v_mfma_f32_16x16x32_bf16 v[10:13], v[166:169], v[244:247], v[10:13]
	v_mfma_f32_16x16x32_bf16 v[2:5], v[174:177], v[244:247], v[2:5]
	s_setprio 0
	s_barrier
	s_add_i32 s10, 0, 0x18000
	s_add_i32 s11, 0, 0x1c000
	v_add_u32_e32 v158, s10, v143
	v_add_u32_e32 v174, s11, v143
	ds_read_b128 v[146:149], v158
	ds_read_b128 v[150:153], v158 offset:1024
	ds_read_b128 v[154:157], v158 offset:2048
	ds_read_b128 v[158:161], v158 offset:3072
	ds_read_b128 v[162:165], v174
	ds_read_b128 v[166:169], v174 offset:1024
	ds_read_b128 v[170:173], v174 offset:2048
	ds_read_b128 v[174:177], v174 offset:3072
	s_add_u32 s100, s54, 0x40000
	s_addc_u32 s101, s55, 0
	s_add_i32 m0, s52, 0x14000
	s_nop 0
	global_load_lds_dwordx4 v0, s[100:101]
	s_add_i32 m0, s52, 0x16000
	s_nop 0
	global_load_lds_dwordx4 v130, s[100:101]
	s_add_u32 s8, s56, 0x40000
	s_addc_u32 s9, s57, 0
	s_mov_b32 m0, s59
	ds_read_b128 v[178:181], v145 offset:32768
	ds_read_b128 v[182:185], v145 offset:33792
	ds_read_b128 v[224:227], v145 offset:34816
	ds_read_b128 v[228:231], v145 offset:35840
	ds_read_b128 v[232:235], v145 offset:36864
	ds_read_b128 v[236:239], v145 offset:37888
	ds_read_b128 v[240:243], v145 offset:38912
	ds_read_b128 v[244:247], v145 offset:39936
	global_load_lds_dwordx4 v134, s[8:9]
	s_mov_b32 m0, s60
	s_nop 0
	global_load_lds_dwordx4 v132, s[8:9]
	s_waitcnt vmcnt(8)
	s_waitcnt lgkmcnt(0)
	s_barrier
	s_setprio 1
	s_waitcnt lgkmcnt(0)
	v_mfma_f32_16x16x32_bf16 v[126:129], v[146:149], v[178:181], v[126:129]
	v_mfma_f32_16x16x32_bf16 v[118:121], v[154:157], v[178:181], v[118:121]
	v_mfma_f32_16x16x32_bf16 v[110:113], v[146:149], v[224:227], v[110:113]
	v_mfma_f32_16x16x32_bf16 v[102:105], v[154:157], v[224:227], v[102:105]
	v_mfma_f32_16x16x32_bf16 v[94:97], v[146:149], v[232:235], v[94:97]
	v_mfma_f32_16x16x32_bf16 v[86:89], v[154:157], v[232:235], v[86:89]
	v_mfma_f32_16x16x32_bf16 v[78:81], v[146:149], v[240:243], v[78:81]
	v_mfma_f32_16x16x32_bf16 v[70:73], v[154:157], v[240:243], v[70:73]
	v_mfma_f32_16x16x32_bf16 v[126:129], v[150:153], v[182:185], v[126:129]
	v_mfma_f32_16x16x32_bf16 v[118:121], v[158:161], v[182:185], v[118:121]
	v_mfma_f32_16x16x32_bf16 v[110:113], v[150:153], v[228:231], v[110:113]
	v_mfma_f32_16x16x32_bf16 v[102:105], v[158:161], v[228:231], v[102:105]
	v_mfma_f32_16x16x32_bf16 v[94:97], v[150:153], v[236:239], v[94:97]
	v_mfma_f32_16x16x32_bf16 v[86:89], v[158:161], v[236:239], v[86:89]
	v_mfma_f32_16x16x32_bf16 v[78:81], v[150:153], v[244:247], v[78:81]
	v_mfma_f32_16x16x32_bf16 v[70:73], v[158:161], v[244:247], v[70:73]
	s_setprio 0
	s_setprio 1
	v_mfma_f32_16x16x32_bf16 v[122:125], v[162:165], v[178:181], v[122:125]
	v_mfma_f32_16x16x32_bf16 v[114:117], v[170:173], v[178:181], v[114:117]
	v_mfma_f32_16x16x32_bf16 v[106:109], v[162:165], v[224:227], v[106:109]
	v_mfma_f32_16x16x32_bf16 v[98:101], v[170:173], v[224:227], v[98:101]
	v_mfma_f32_16x16x32_bf16 v[90:93], v[162:165], v[232:235], v[90:93]
	v_mfma_f32_16x16x32_bf16 v[82:85], v[170:173], v[232:235], v[82:85]
	v_mfma_f32_16x16x32_bf16 v[74:77], v[162:165], v[240:243], v[74:77]
	v_mfma_f32_16x16x32_bf16 v[66:69], v[170:173], v[240:243], v[66:69]
	v_mfma_f32_16x16x32_bf16 v[122:125], v[166:169], v[182:185], v[122:125]
	v_mfma_f32_16x16x32_bf16 v[114:117], v[174:177], v[182:185], v[114:117]
	v_mfma_f32_16x16x32_bf16 v[106:109], v[166:169], v[228:231], v[106:109]
	v_mfma_f32_16x16x32_bf16 v[98:101], v[174:177], v[228:231], v[98:101]
	v_mfma_f32_16x16x32_bf16 v[90:93], v[166:169], v[236:239], v[90:93]
	v_mfma_f32_16x16x32_bf16 v[82:85], v[174:177], v[236:239], v[82:85]
	v_mfma_f32_16x16x32_bf16 v[74:77], v[166:169], v[244:247], v[74:77]
	v_mfma_f32_16x16x32_bf16 v[66:69], v[174:177], v[244:247], v[66:69]
	s_setprio 0
	s_barrier
	s_add_i32 s8, s10, s52
	s_add_u32 s100, s54, 0x80
	s_addc_u32 s101, s55, 0
	s_mov_b32 m0, s8
	ds_read_b128 v[178:181], v145 offset:49152
	ds_read_b128 v[182:185], v145 offset:50176
	ds_read_b128 v[224:227], v145 offset:51200
	ds_read_b128 v[228:231], v145 offset:52224
	ds_read_b128 v[232:235], v145 offset:53248
	ds_read_b128 v[236:239], v145 offset:54272
	ds_read_b128 v[240:243], v145 offset:55296
	ds_read_b128 v[244:247], v145 offset:56320
	global_load_lds_dwordx4 v0, s[100:101]
	s_add_i32 m0, s8, 0x2000
	global_load_lds_dwordx4 v130, s[100:101]
	s_add_u32 s100, s54, 0x40080
	s_addc_u32 s101, s55, 0
	s_add_u32 vcc_lo, s56, 0x80
	s_addc_u32 vcc_hi, s57, 0
	s_mov_b32 m0, s61
	s_nop 0
	global_load_lds_dwordx4 v134, vcc
	s_mov_b32 m0, s62
	s_nop 0
	global_load_lds_dwordx4 v132, vcc
	s_waitcnt vmcnt(6)
	s_waitcnt lgkmcnt(0)
	s_barrier
	s_setprio 1
	s_waitcnt lgkmcnt(0)
	v_mfma_f32_16x16x32_bf16 v[62:65], v[146:149], v[178:181], v[62:65]
	v_mfma_f32_16x16x32_bf16 v[54:57], v[154:157], v[178:181], v[54:57]
	v_mfma_f32_16x16x32_bf16 v[46:49], v[146:149], v[224:227], v[46:49]
	v_mfma_f32_16x16x32_bf16 v[38:41], v[154:157], v[224:227], v[38:41]
	v_mfma_f32_16x16x32_bf16 v[30:33], v[146:149], v[232:235], v[30:33]
	v_mfma_f32_16x16x32_bf16 v[22:25], v[154:157], v[232:235], v[22:25]
	v_mfma_f32_16x16x32_bf16 v[14:17], v[146:149], v[240:243], v[14:17]
	v_mfma_f32_16x16x32_bf16 v[6:9], v[154:157], v[240:243], v[6:9]
	v_mfma_f32_16x16x32_bf16 v[62:65], v[150:153], v[182:185], v[62:65]
	v_mfma_f32_16x16x32_bf16 v[54:57], v[158:161], v[182:185], v[54:57]
	v_mfma_f32_16x16x32_bf16 v[46:49], v[150:153], v[228:231], v[46:49]
	v_mfma_f32_16x16x32_bf16 v[38:41], v[158:161], v[228:231], v[38:41]
	v_mfma_f32_16x16x32_bf16 v[30:33], v[150:153], v[236:239], v[30:33]
	v_mfma_f32_16x16x32_bf16 v[22:25], v[158:161], v[236:239], v[22:25]
	v_mfma_f32_16x16x32_bf16 v[14:17], v[150:153], v[244:247], v[14:17]
	v_mfma_f32_16x16x32_bf16 v[6:9], v[158:161], v[244:247], v[6:9]
	s_setprio 0
	s_setprio 1
	v_mfma_f32_16x16x32_bf16 v[58:61], v[162:165], v[178:181], v[58:61]
	v_mfma_f32_16x16x32_bf16 v[50:53], v[170:173], v[178:181], v[50:53]
	v_mfma_f32_16x16x32_bf16 v[42:45], v[162:165], v[224:227], v[42:45]
	v_mfma_f32_16x16x32_bf16 v[34:37], v[170:173], v[224:227], v[34:37]
	v_mfma_f32_16x16x32_bf16 v[26:29], v[162:165], v[232:235], v[26:29]
	v_mfma_f32_16x16x32_bf16 v[18:21], v[170:173], v[232:235], v[18:21]
	v_mfma_f32_16x16x32_bf16 v[10:13], v[162:165], v[240:243], v[10:13]
	v_mfma_f32_16x16x32_bf16 v[2:5], v[170:173], v[240:243], v[2:5]
	v_mfma_f32_16x16x32_bf16 v[58:61], v[166:169], v[182:185], v[58:61]
	v_mfma_f32_16x16x32_bf16 v[50:53], v[174:177], v[182:185], v[50:53]
	v_mfma_f32_16x16x32_bf16 v[42:45], v[166:169], v[228:231], v[42:45]
	v_mfma_f32_16x16x32_bf16 v[34:37], v[174:177], v[228:231], v[34:37]
	v_mfma_f32_16x16x32_bf16 v[26:29], v[166:169], v[236:239], v[26:29]
	v_mfma_f32_16x16x32_bf16 v[18:21], v[174:177], v[236:239], v[18:21]
	v_mfma_f32_16x16x32_bf16 v[10:13], v[166:169], v[244:247], v[10:13]
	v_mfma_f32_16x16x32_bf16 v[2:5], v[174:177], v[244:247], v[2:5]
	s_setprio 0
	s_barrier
	s_add_i32 s72, s72, 2
	s_add_u32 s50, s50, 0x100
	s_addc_u32 s51, s51, 0
	s_add_u32 s68, s68, 0x100
	s_addc_u32 s69, s69, 0
	s_cmp_gt_u32 s72, 13
	s_cbranch_scc0 .LBB0_120
	s_and_b64 vcc, exec, s[24:25]
	s_mov_b64 s[68:69], s[36:37]
	s_cbranch_vccz .LBB0_123
	s_barrier
